# window loop: exp2 argument by one fma per element (as in the other branches)
# baseline (speedup 1.0000x reference)
; #define LAS __attribute__((address_space(3)))
; __device__ __forceinline__ float fexp(float x) { return __expf(x); }
; template <int MODE>
; __device__ __forceinline__ void softmax_block(f32x4 (&acc)[4], int base, bool ok, int t, int g4, const LAS float* lutg, SmState& st, f32x4 (&O)[4], bf16x8 (&pB)[2]) {
;     float mx = -1e30f; unsigned vm = 0u;
; #pragma unroll
;     for (int nt = 0; nt < 4; ++nt)
; #pragma unroll
;         for (int i = 0; i < 4; ++i) {
;             const int key = base + 16 * nt + 4 * g4 + i;
;             const int dist = (MODE == 0) ? t - (16 * key + 31) : t - key;
;             bool valid = dist >= 0;
;             if (MODE == 1) valid = valid && ok;
;             if (MODE == 2) valid = valid && dist < 512;
;             int dc = dist < 0 ? 0 : dist; dc = dc > 1023 ? 1023 : dc;
;             const float lg = acc[nt][i] + lutg[dc * 4];
;             acc[nt][i] = lg;
;             if (valid) { mx = fmaxf(mx, lg); vm |= 1u << (nt * 4 + i); }
;         }
;     mx = fmaxf(mx, __shfl_xor(mx, 16)); mx = fmaxf(mx, __shfl_xor(mx, 32));
;     const float mn = fmaxf(st.m, mx);
;     const float sc = fexp(st.m - mn);
;     float ls = 0.f;
; #pragma unroll
;     for (int nt = 0; nt < 4; ++nt)
; #pragma unroll
;         for (int i = 0; i < 4; ++i) { const float p = ((vm >> (nt * 4 + i)) & 1u) ? fexp(acc[nt][i] - mn) : 0.f; acc[nt][i] = p; ls += p; }
;     st.l = st.l * sc + ls; st.m = mn;
.Lwin_nokpf:
	s_waitcnt lgkmcnt(0)
	s_nop 7
	v_add_f32_e32 v228, v228, v244
	v_add_f32_e32 v229, v229, v245
	v_add_f32_e32 v230, v230, v246
	v_add_f32_e32 v231, v231, v247
	v_add_f32_e32 v232, v232, v248
	v_add_f32_e32 v233, v233, v249
	v_add_f32_e32 v234, v234, v250
	v_add_f32_e32 v235, v235, v251
	v_add_f32_e32 v236, v236, v252
	v_add_f32_e32 v237, v237, v253
	v_add_f32_e32 v238, v238, v210
	v_add_f32_e32 v239, v239, v211
	v_add_f32_e32 v240, v240, v212
	v_add_f32_e32 v241, v241, v213
	v_add_f32_e32 v242, v242, v144
	v_add_f32_e32 v243, v243, v255
	s_cmp_lg_u32 s17, 0
	s_cbranch_scc0 .Lwin_sm_gen
	v_max3_f32 v244, v228, v229, v230
	v_max3_f32 v247, v231, v232, v233
	v_max3_f32 v250, v234, v235, v236
	v_max3_f32 v253, v237, v238, v239
	v_max3_f32 v212, v240, v241, v242
	v_max3_f32 v244, v244, v247, v250
	v_max3_f32 v253, v253, v212, v243
	v_max_f32_e32 v244, v244, v253
	v_mov_b32_e32 v127, v244
	s_nop 1
	v_permlane16_swap_b32_e32 v244, v127
	v_max_f32_e32 v244, v244, v127
	v_mov_b32_e32 v127, v244
	s_nop 1
	v_permlane32_swap_b32_e32 v244, v127
	v_max3_f32 v214, v103, v244, v127
	v_sub_f32_e32 v150, v103, v214
	v_mul_f32_e32 v127, 0xbfb8aa3b, v214
	v_mul_f32_e32 v150, 0x3fb8aa3b, v150
	v_fmamk_f32 v228, v228, 0x3fb8aa3b, v127
	v_fmamk_f32 v229, v229, 0x3fb8aa3b, v127
	v_fmamk_f32 v230, v230, 0x3fb8aa3b, v127
	v_fmamk_f32 v231, v231, 0x3fb8aa3b, v127
	v_fmamk_f32 v232, v232, 0x3fb8aa3b, v127
	v_fmamk_f32 v233, v233, 0x3fb8aa3b, v127
	v_fmamk_f32 v234, v234, 0x3fb8aa3b, v127
	v_fmamk_f32 v235, v235, 0x3fb8aa3b, v127
	v_fmamk_f32 v236, v236, 0x3fb8aa3b, v127
	v_fmamk_f32 v237, v237, 0x3fb8aa3b, v127
	v_fmamk_f32 v238, v238, 0x3fb8aa3b, v127
	v_fmamk_f32 v239, v239, 0x3fb8aa3b, v127
	v_fmamk_f32 v240, v240, 0x3fb8aa3b, v127
	v_fmamk_f32 v241, v241, 0x3fb8aa3b, v127
	v_fmamk_f32 v242, v242, 0x3fb8aa3b, v127
	v_fmamk_f32 v243, v243, 0x3fb8aa3b, v127
	v_exp_f32_e32 v150, v150
	v_exp_f32_e32 v228, v228
	v_exp_f32_e32 v229, v229
	v_exp_f32_e32 v230, v230
	v_exp_f32_e32 v231, v231
	v_exp_f32_e32 v232, v232
	v_exp_f32_e32 v233, v233
	v_exp_f32_e32 v234, v234
	v_exp_f32_e32 v235, v235
	v_exp_f32_e32 v236, v236
	v_exp_f32_e32 v237, v237
	v_exp_f32_e32 v238, v238
	v_exp_f32_e32 v239, v239
	v_exp_f32_e32 v240, v240
	v_exp_f32_e32 v241, v241
	v_exp_f32_e32 v242, v242
	v_exp_f32_e32 v243, v243
	v_mov_b32_e32 v103, v214
	s_branch .Lwin_sm_done
.Lwin_sm_gen:
	v_cndmask_b32_e64 v244, v182, v228, s[46:47]
	v_cndmask_b32_e64 v245, v182, v229, s[48:49]
	v_cndmask_b32_e64 v246, v182, v230, s[50:51]
	v_cndmask_b32_e64 v247, v182, v231, s[52:53]
	v_cndmask_b32_e64 v248, v182, v232, s[54:55]
	v_cndmask_b32_e64 v249, v182, v233, s[56:57]
	v_cndmask_b32_e64 v250, v182, v234, s[58:59]
	v_cndmask_b32_e64 v251, v182, v235, s[60:61]
	v_cndmask_b32_e64 v252, v182, v236, s[62:63]
	v_cndmask_b32_e64 v253, v182, v237, s[64:65]
	v_cndmask_b32_e64 v210, v182, v238, s[66:67]
	v_cndmask_b32_e64 v211, v182, v239, s[68:69]
	v_cndmask_b32_e64 v212, v182, v240, s[96:97]
	v_cndmask_b32_e64 v213, v182, v241, s[98:99]
	v_cndmask_b32_e64 v144, v182, v242, s[100:101]
	v_cndmask_b32_e64 v255, v182, v243, s[22:23]
	v_max3_f32 v244, v244, v245, v246
	v_max3_f32 v247, v247, v248, v249
	v_max3_f32 v250, v250, v251, v252
	v_max3_f32 v253, v253, v210, v211
	v_max3_f32 v212, v212, v213, v144
	v_max3_f32 v244, v244, v247, v250
	v_max3_f32 v253, v253, v212, v255
	v_max_f32_e32 v244, v244, v253
	v_mov_b32_e32 v127, v244
	s_nop 1
	v_permlane16_swap_b32_e32 v244, v127
	v_max_f32_e32 v244, v244, v127
	v_mov_b32_e32 v127, v244
	s_nop 1
	v_permlane32_swap_b32_e32 v244, v127
	v_max3_f32 v214, v103, v244, v127
	v_sub_f32_e32 v150, v103, v214
	v_mul_f32_e32 v127, 0xbfb8aa3b, v214
	v_mul_f32_e32 v150, 0x3fb8aa3b, v150
	v_fmamk_f32 v228, v228, 0x3fb8aa3b, v127
	v_fmamk_f32 v229, v229, 0x3fb8aa3b, v127
	v_fmamk_f32 v230, v230, 0x3fb8aa3b, v127
	v_fmamk_f32 v231, v231, 0x3fb8aa3b, v127
	v_fmamk_f32 v232, v232, 0x3fb8aa3b, v127
	v_fmamk_f32 v233, v233, 0x3fb8aa3b, v127
	v_fmamk_f32 v234, v234, 0x3fb8aa3b, v127
	v_fmamk_f32 v235, v235, 0x3fb8aa3b, v127
	v_fmamk_f32 v236, v236, 0x3fb8aa3b, v127
	v_fmamk_f32 v237, v237, 0x3fb8aa3b, v127
	v_fmamk_f32 v238, v238, 0x3fb8aa3b, v127
	v_fmamk_f32 v239, v239, 0x3fb8aa3b, v127
	v_fmamk_f32 v240, v240, 0x3fb8aa3b, v127
	v_fmamk_f32 v241, v241, 0x3fb8aa3b, v127
	v_fmamk_f32 v242, v242, 0x3fb8aa3b, v127
	v_fmamk_f32 v243, v243, 0x3fb8aa3b, v127
	v_exp_f32_e32 v150, v150
	v_exp_f32_e32 v228, v228
	v_exp_f32_e32 v229, v229
	v_exp_f32_e32 v230, v230
	v_exp_f32_e32 v231, v231
	v_exp_f32_e32 v232, v232
	v_exp_f32_e32 v233, v233
	v_exp_f32_e32 v234, v234
	v_exp_f32_e32 v235, v235
	v_exp_f32_e32 v236, v236
	v_exp_f32_e32 v237, v237
	v_exp_f32_e32 v238, v238
	v_exp_f32_e32 v239, v239
	v_exp_f32_e32 v240, v240
	v_exp_f32_e32 v241, v241
	v_exp_f32_e32 v242, v242
	v_exp_f32_e32 v243, v243
	v_mov_b32_e32 v103, v214
	v_cndmask_b32_e64 v228, 0, v228, s[46:47]
	v_cndmask_b32_e64 v229, 0, v229, s[48:49]
	v_cndmask_b32_e64 v230, 0, v230, s[50:51]
	v_cndmask_b32_e64 v231, 0, v231, s[52:53]
	v_cndmask_b32_e64 v232, 0, v232, s[54:55]
	v_cndmask_b32_e64 v233, 0, v233, s[56:57]
	v_cndmask_b32_e64 v234, 0, v234, s[58:59]
	v_cndmask_b32_e64 v235, 0, v235, s[60:61]
	v_cndmask_b32_e64 v236, 0, v236, s[62:63]
	v_cndmask_b32_e64 v237, 0, v237, s[64:65]
	v_cndmask_b32_e64 v238, 0, v238, s[66:67]
	v_cndmask_b32_e64 v239, 0, v239, s[68:69]
	v_cndmask_b32_e64 v240, 0, v240, s[96:97]
	v_cndmask_b32_e64 v241, 0, v241, s[98:99]
	v_cndmask_b32_e64 v242, 0, v242, s[100:101]
	v_cndmask_b32_e64 v243, 0, v243, s[22:23]
